# xcd barrier: released workgroups poll the cross-XCC generation word directly (one release level instead of two), leader's per-XCC generation bump dropped; on top of seam0
# baseline (speedup 1.0000x reference)
; __device__ __forceinline__ unsigned xb_ld(unsigned* p)              { return __hip_atomic_load(p, __ATOMIC_RELAXED, __HIP_MEMORY_SCOPE_AGENT); }
; __device__ __forceinline__ unsigned xb_add(unsigned* p, unsigned v) { return __hip_atomic_fetch_add(p, v, __ATOMIC_RELAXED, __HIP_MEMORY_SCOPE_AGENT); }
; #define XB_SPIN(cond, bar) do { unsigned _sp = 0; while (cond) { __builtin_amdgcn_s_sleep(1); \
;     if ((++_sp & 255u) == 0u) { if (xb_ld(&(bar)[XB_TMO])) break; if (_sp > XB_SPIN_CAP) { atomicAdd(&(bar)[XB_TMO], 1u); break; } } } } while (0)
; __device__ __forceinline__ void xcd_barrier(const XcdBarrier& b) {
;     ...
;         const unsigned old = xb_add(&bar[XB_XSUB(b.x)], 1u);
;         const unsigned gen = old / nloc;
;         if (old + 1u == (gen + 1u) * nloc) {
;             __builtin_amdgcn_fence(__ATOMIC_RELEASE, "agent");
;             asm volatile("s_waitcnt vmcnt(0)" ::: "memory");
;             const unsigned og = xb_add(&bar[XB_TOP], 1u);
;             const unsigned tg = og / nx;
;             if (og + 1u == (tg + 1u) * nx) xb_add(&bar[XB_TOPGEN], 1u);
;             else XB_SPIN(xb_ld(&bar[XB_TOPGEN]) == tg, bar);
;             __builtin_amdgcn_fence(__ATOMIC_ACQUIRE, "agent");
;             xb_add(&bar[XB_XGEN(b.x)], 1u);
;             asm volatile("s_waitcnt vmcnt(0)" ::: "memory");
;         } else {
;             XB_SPIN(xb_ld(&bar[XB_XGEN(b.x)]) == gen, bar);
;             __builtin_amdgcn_fence(__ATOMIC_ACQUIRE, "agent");
;             asm volatile("s_waitcnt vmcnt(0)" ::: "memory");
;         }
.LBB0_442:
	s_or_b64 exec, exec, s[10:11]
	v_cvt_f32_u32_e32 v4, v2
	s_waitcnt vmcnt(0)
	v_readfirstlane_b32 s3, v3
	v_sub_u32_e32 v3, 0, v2
	v_rcp_iflag_f32_e32 v4, v4
	v_add_u32_e32 v5, s3, v1
	v_mul_f32_e32 v4, 0x4f7ffffe, v4
	v_cvt_u32_f32_e32 v4, v4
	v_mul_lo_u32 v1, v3, v4
	v_mul_hi_u32 v1, v4, v1
	v_add_u32_e32 v1, v4, v1
	v_mul_hi_u32 v1, v5, v1
	v_mul_lo_u32 v3, v1, v2
	v_sub_u32_e32 v3, v5, v3
	v_add_u32_e32 v4, 1, v1
	v_cmp_ge_u32_e32 vcc, v3, v2
	s_nop 1
	v_cndmask_b32_e32 v1, v1, v4, vcc
	v_sub_u32_e32 v4, v3, v2
	v_cndmask_b32_e32 v3, v3, v4, vcc
	v_add_u32_e32 v4, 1, v1
	v_cmp_ge_u32_e32 vcc, v3, v2
	v_add_u32_e32 v3, 1, v5
	s_nop 0
	v_cndmask_b32_e32 v1, v1, v4, vcc
	v_mul_lo_u32 v4, v2, v1
	v_add_u32_e32 v2, v4, v2
	v_cmp_ne_u32_e32 vcc, v3, v2
	s_and_saveexec_b64 s[8:9], vcc
	s_xor_b64 s[8:9], exec, s[8:9]
	s_cbranch_execz .LBB0_456
	s_waitcnt lgkmcnt(0)
	s_add_u32 s14, s28, 0x8703500
	s_addc_u32 s15, s29, 0
	v_mov_b32_e32 v0, 0
	global_load_dword v0, v0, s[14:15] sc1
	s_waitcnt vmcnt(0)
	v_cmp_eq_u32_e32 vcc, v0, v1
	s_and_saveexec_b64 s[10:11], vcc
	s_cbranch_execz .LBB0_455
	s_add_u32 s12, s28, 0x8700200
	s_addc_u32 s13, s29, 0
	s_mov_b32 s3, 1
	s_mov_b64 s[16:17], 0
	v_mov_b32_e32 v0, 0
	s_branch .LBB0_446

; __device__ __forceinline__ unsigned xb_ld(unsigned* p)              { return __hip_atomic_load(p, __ATOMIC_RELAXED, __HIP_MEMORY_SCOPE_AGENT); }
; __device__ __forceinline__ unsigned xb_add(unsigned* p, unsigned v) { return __hip_atomic_fetch_add(p, v, __ATOMIC_RELAXED, __HIP_MEMORY_SCOPE_AGENT); }
; #define XB_SPIN(cond, bar) do { unsigned _sp = 0; while (cond) { __builtin_amdgcn_s_sleep(1); \
;     if ((++_sp & 255u) == 0u) { if (xb_ld(&(bar)[XB_TMO])) break; if (_sp > XB_SPIN_CAP) { atomicAdd(&(bar)[XB_TMO], 1u); break; } } } } while (0)
; __device__ __forceinline__ void xcd_barrier(const XcdBarrier& b) {
;     ...
;         if (old + 1u == (gen + 1u) * nloc) {
;             __builtin_amdgcn_fence(__ATOMIC_RELEASE, "agent");
;             asm volatile("s_waitcnt vmcnt(0)" ::: "memory");
;             const unsigned og = xb_add(&bar[XB_TOP], 1u);
;             const unsigned tg = og / nx;
;             if (og + 1u == (tg + 1u) * nx) xb_add(&bar[XB_TOPGEN], 1u);
;             else XB_SPIN(xb_ld(&bar[XB_TOPGEN]) == tg, bar);
;             __builtin_amdgcn_fence(__ATOMIC_ACQUIRE, "agent");
;             xb_add(&bar[XB_XGEN(b.x)], 1u);
;             asm volatile("s_waitcnt vmcnt(0)" ::: "memory");
.LBB0_473:
	s_or_b64 exec, exec, s[8:9]
	s_mov_b64 s[8:9], exec
	v_mbcnt_lo_u32_b32 v0, s8, 0
	v_mbcnt_hi_u32_b32 v0, s9, v0
	v_cmp_eq_u32_e32 vcc, 0, v0
	s_waitcnt vmcnt(0)
	buffer_inv sc1
	s_and_saveexec_b64 s[10:11], vcc
	s_cbranch_execz .LBB0_475
	s_bcnt1_i32_b64 s3, s[8:9]
	v_mov_b32_e32 v0, 0x2000
	v_mov_b32_e32 v1, s3
.LBB0_475:
	s_or_b64 exec, exec, s[10:11]
	s_waitcnt vmcnt(0)

; __device__ __forceinline__ unsigned xb_ld(unsigned* p)              { return __hip_atomic_load(p, __ATOMIC_RELAXED, __HIP_MEMORY_SCOPE_AGENT); }
; __device__ __forceinline__ unsigned xb_add(unsigned* p, unsigned v) { return __hip_atomic_fetch_add(p, v, __ATOMIC_RELAXED, __HIP_MEMORY_SCOPE_AGENT); }
; #define XB_SPIN(cond, bar) do { unsigned _sp = 0; while (cond) { __builtin_amdgcn_s_sleep(1); \
;     if ((++_sp & 255u) == 0u) { if (xb_ld(&(bar)[XB_TMO])) break; if (_sp > XB_SPIN_CAP) { atomicAdd(&(bar)[XB_TMO], 1u); break; } } } } while (0)
; __device__ __forceinline__ void xcd_barrier(const XcdBarrier& b) {
;     ...
;         if (old + 1u == (gen + 1u) * nloc) {
;             __builtin_amdgcn_fence(__ATOMIC_RELEASE, "agent");
;             asm volatile("s_waitcnt vmcnt(0)" ::: "memory");
;             const unsigned og = xb_add(&bar[XB_TOP], 1u);
;             const unsigned tg = og / nx;
;             if (og + 1u == (tg + 1u) * nx) xb_add(&bar[XB_TOPGEN], 1u);
;             else XB_SPIN(xb_ld(&bar[XB_TOPGEN]) == tg, bar);
;             __builtin_amdgcn_fence(__ATOMIC_ACQUIRE, "agent");
;             xb_add(&bar[XB_XGEN(b.x)], 1u);
;             asm volatile("s_waitcnt vmcnt(0)" ::: "memory");
.LBB0_898:
	s_or_b64 exec, exec, s[8:9]
	s_mov_b64 s[8:9], exec
	v_mbcnt_lo_u32_b32 v0, s8, 0
	v_mbcnt_hi_u32_b32 v0, s9, v0
	v_cmp_eq_u32_e32 vcc, 0, v0
	s_waitcnt vmcnt(0)
	buffer_inv sc1
	s_and_saveexec_b64 s[10:11], vcc
	s_cbranch_execz .LBB0_900
	s_bcnt1_i32_b64 s3, s[8:9]
	v_mov_b32_e32 v0, 0x2000
	v_mov_b32_e32 v1, s3
.LBB0_900:
	s_or_b64 exec, exec, s[10:11]
	s_waitcnt vmcnt(0)

; __device__ __forceinline__ unsigned xb_ld(unsigned* p)              { return __hip_atomic_load(p, __ATOMIC_RELAXED, __HIP_MEMORY_SCOPE_AGENT); }
; __device__ __forceinline__ unsigned xb_add(unsigned* p, unsigned v) { return __hip_atomic_fetch_add(p, v, __ATOMIC_RELAXED, __HIP_MEMORY_SCOPE_AGENT); }
; #define XB_SPIN(cond, bar) do { unsigned _sp = 0; while (cond) { __builtin_amdgcn_s_sleep(1); \
;     if ((++_sp & 255u) == 0u) { if (xb_ld(&(bar)[XB_TMO])) break; if (_sp > XB_SPIN_CAP) { atomicAdd(&(bar)[XB_TMO], 1u); break; } } } } while (0)
; __device__ __forceinline__ void xcd_barrier(const XcdBarrier& b) {
;     ...
;         const unsigned old = xb_add(&bar[XB_XSUB(b.x)], 1u);
;         const unsigned gen = old / nloc;
;         if (old + 1u == (gen + 1u) * nloc) {
;             __builtin_amdgcn_fence(__ATOMIC_RELEASE, "agent");
;             asm volatile("s_waitcnt vmcnt(0)" ::: "memory");
;             const unsigned og = xb_add(&bar[XB_TOP], 1u);
;             const unsigned tg = og / nx;
;             if (og + 1u == (tg + 1u) * nx) xb_add(&bar[XB_TOPGEN], 1u);
;             else XB_SPIN(xb_ld(&bar[XB_TOPGEN]) == tg, bar);
;             __builtin_amdgcn_fence(__ATOMIC_ACQUIRE, "agent");
;             xb_add(&bar[XB_XGEN(b.x)], 1u);
;             asm volatile("s_waitcnt vmcnt(0)" ::: "memory");
;         } else {
;             XB_SPIN(xb_ld(&bar[XB_XGEN(b.x)]) == gen, bar);
;             __builtin_amdgcn_fence(__ATOMIC_ACQUIRE, "agent");
;             asm volatile("s_waitcnt vmcnt(0)" ::: "memory");
;         }
.LBB0_1013:
	s_or_b64 exec, exec, s[8:9]
	v_cvt_f32_u32_e32 v4, v2
	s_waitcnt vmcnt(0)
	v_readfirstlane_b32 s3, v3
	v_sub_u32_e32 v3, 0, v2
	v_rcp_iflag_f32_e32 v4, v4
	v_add_u32_e32 v5, s3, v1
	v_mul_f32_e32 v4, 0x4f7ffffe, v4
	v_cvt_u32_f32_e32 v4, v4
	v_mul_lo_u32 v1, v3, v4
	v_mul_hi_u32 v1, v4, v1
	v_add_u32_e32 v1, v4, v1
	v_mul_hi_u32 v1, v5, v1
	v_mul_lo_u32 v3, v1, v2
	v_sub_u32_e32 v3, v5, v3
	v_add_u32_e32 v4, 1, v1
	v_cmp_ge_u32_e32 vcc, v3, v2
	s_nop 1
	v_cndmask_b32_e32 v1, v1, v4, vcc
	v_sub_u32_e32 v4, v3, v2
	v_cndmask_b32_e32 v3, v3, v4, vcc
	v_add_u32_e32 v4, 1, v1
	v_cmp_ge_u32_e32 vcc, v3, v2
	v_add_u32_e32 v3, 1, v5
	s_nop 0
	v_cndmask_b32_e32 v1, v1, v4, vcc
	v_mul_lo_u32 v4, v2, v1
	v_add_u32_e32 v2, v4, v2
	v_cmp_ne_u32_e32 vcc, v3, v2
	s_and_saveexec_b64 s[6:7], vcc
	s_xor_b64 s[6:7], exec, s[6:7]
	s_cbranch_execz .LBB0_1027
	s_waitcnt lgkmcnt(0)
	s_add_u32 s12, s28, 0x8703500
	s_addc_u32 s13, s29, 0
	v_mov_b32_e32 v0, 0
	global_load_dword v0, v0, s[12:13] sc1
	s_waitcnt vmcnt(0)
	v_cmp_eq_u32_e32 vcc, v0, v1
	s_and_saveexec_b64 s[8:9], vcc
	s_cbranch_execz .LBB0_1026
	s_add_u32 s10, s28, 0x8700200
	s_addc_u32 s11, s29, 0
	s_mov_b32 s3, 1
	s_mov_b64 s[14:15], 0
	v_mov_b32_e32 v0, 0
	s_branch .LBB0_1017

; __device__ __forceinline__ unsigned xb_ld(unsigned* p)              { return __hip_atomic_load(p, __ATOMIC_RELAXED, __HIP_MEMORY_SCOPE_AGENT); }
; __device__ __forceinline__ unsigned xb_add(unsigned* p, unsigned v) { return __hip_atomic_fetch_add(p, v, __ATOMIC_RELAXED, __HIP_MEMORY_SCOPE_AGENT); }
; #define XB_SPIN(cond, bar) do { unsigned _sp = 0; while (cond) { __builtin_amdgcn_s_sleep(1); \
;     if ((++_sp & 255u) == 0u) { if (xb_ld(&(bar)[XB_TMO])) break; if (_sp > XB_SPIN_CAP) { atomicAdd(&(bar)[XB_TMO], 1u); break; } } } } while (0)
; __device__ __forceinline__ void xcd_barrier(const XcdBarrier& b) {
;     ...
;         if (old + 1u == (gen + 1u) * nloc) {
;             __builtin_amdgcn_fence(__ATOMIC_RELEASE, "agent");
;             asm volatile("s_waitcnt vmcnt(0)" ::: "memory");
;             const unsigned og = xb_add(&bar[XB_TOP], 1u);
;             const unsigned tg = og / nx;
;             if (og + 1u == (tg + 1u) * nx) xb_add(&bar[XB_TOPGEN], 1u);
;             else XB_SPIN(xb_ld(&bar[XB_TOPGEN]) == tg, bar);
;             __builtin_amdgcn_fence(__ATOMIC_ACQUIRE, "agent");
;             xb_add(&bar[XB_XGEN(b.x)], 1u);
;             asm volatile("s_waitcnt vmcnt(0)" ::: "memory");
.LBB0_1044:
	s_or_b64 exec, exec, s[6:7]
	s_mov_b64 s[6:7], exec
	v_mbcnt_lo_u32_b32 v0, s6, 0
	v_mbcnt_hi_u32_b32 v0, s7, v0
	v_cmp_eq_u32_e32 vcc, 0, v0
	s_waitcnt vmcnt(0)
	buffer_inv sc1
	s_and_saveexec_b64 s[8:9], vcc
	s_cbranch_execz .LBB0_1046
	s_bcnt1_i32_b64 s3, s[6:7]
	v_mov_b32_e32 v0, 0x2000
	v_mov_b32_e32 v1, s3
.LBB0_1046:
	s_or_b64 exec, exec, s[8:9]
	s_waitcnt vmcnt(0)

; __device__ __forceinline__ unsigned xb_ld(unsigned* p)              { return __hip_atomic_load(p, __ATOMIC_RELAXED, __HIP_MEMORY_SCOPE_AGENT); }
; __device__ __forceinline__ unsigned xb_add(unsigned* p, unsigned v) { return __hip_atomic_fetch_add(p, v, __ATOMIC_RELAXED, __HIP_MEMORY_SCOPE_AGENT); }
; #define XB_SPIN(cond, bar) do { unsigned _sp = 0; while (cond) { __builtin_amdgcn_s_sleep(1); \
;     if ((++_sp & 255u) == 0u) { if (xb_ld(&(bar)[XB_TMO])) break; if (_sp > XB_SPIN_CAP) { atomicAdd(&(bar)[XB_TMO], 1u); break; } } } } while (0)
; __device__ __forceinline__ void xcd_barrier(const XcdBarrier& b) {
;     ...
;         if (old + 1u == (gen + 1u) * nloc) {
;             __builtin_amdgcn_fence(__ATOMIC_RELEASE, "agent");
;             asm volatile("s_waitcnt vmcnt(0)" ::: "memory");
;             const unsigned og = xb_add(&bar[XB_TOP], 1u);
;             const unsigned tg = og / nx;
;             if (og + 1u == (tg + 1u) * nx) xb_add(&bar[XB_TOPGEN], 1u);
;             else XB_SPIN(xb_ld(&bar[XB_TOPGEN]) == tg, bar);
;             __builtin_amdgcn_fence(__ATOMIC_ACQUIRE, "agent");
;             xb_add(&bar[XB_XGEN(b.x)], 1u);
;             asm volatile("s_waitcnt vmcnt(0)" ::: "memory");
.LBB0_1130:
	s_or_b64 exec, exec, s[8:9]
	s_mov_b64 s[8:9], exec
	v_mbcnt_lo_u32_b32 v0, s8, 0
	v_mbcnt_hi_u32_b32 v0, s9, v0
	v_cmp_eq_u32_e32 vcc, 0, v0
	s_waitcnt vmcnt(0)
	buffer_inv sc1
	s_and_saveexec_b64 s[10:11], vcc
	s_cbranch_execz .LBB0_1132
	s_bcnt1_i32_b64 s3, s[8:9]
	v_mov_b32_e32 v0, 0x2000
	v_mov_b32_e32 v1, s3
.LBB0_1132:
	s_or_b64 exec, exec, s[10:11]
	s_waitcnt vmcnt(0)

; __device__ __forceinline__ unsigned xb_ld(unsigned* p)              { return __hip_atomic_load(p, __ATOMIC_RELAXED, __HIP_MEMORY_SCOPE_AGENT); }
; __device__ __forceinline__ unsigned xb_add(unsigned* p, unsigned v) { return __hip_atomic_fetch_add(p, v, __ATOMIC_RELAXED, __HIP_MEMORY_SCOPE_AGENT); }
; #define XB_SPIN(cond, bar) do { unsigned _sp = 0; while (cond) { __builtin_amdgcn_s_sleep(1); \
;     if ((++_sp & 255u) == 0u) { if (xb_ld(&(bar)[XB_TMO])) break; if (_sp > XB_SPIN_CAP) { atomicAdd(&(bar)[XB_TMO], 1u); break; } } } } while (0)
; __device__ __forceinline__ void xcd_barrier(const XcdBarrier& b) {
;     ...
;         if (old + 1u == (gen + 1u) * nloc) {
;             __builtin_amdgcn_fence(__ATOMIC_RELEASE, "agent");
;             asm volatile("s_waitcnt vmcnt(0)" ::: "memory");
;             const unsigned og = xb_add(&bar[XB_TOP], 1u);
;             const unsigned tg = og / nx;
;             if (og + 1u == (tg + 1u) * nx) xb_add(&bar[XB_TOPGEN], 1u);
;             else XB_SPIN(xb_ld(&bar[XB_TOPGEN]) == tg, bar);
;             __builtin_amdgcn_fence(__ATOMIC_ACQUIRE, "agent");
;             xb_add(&bar[XB_XGEN(b.x)], 1u);
;             asm volatile("s_waitcnt vmcnt(0)" ::: "memory");
.LBB0_1343:
	s_or_b64 exec, exec, s[8:9]
	s_mov_b64 s[8:9], exec
	v_mbcnt_lo_u32_b32 v0, s8, 0
	v_mbcnt_hi_u32_b32 v0, s9, v0
	v_cmp_eq_u32_e32 vcc, 0, v0
	s_waitcnt vmcnt(0)
	buffer_inv sc1
	s_and_saveexec_b64 s[10:11], vcc
	s_cbranch_execz .LBB0_1345
	s_bcnt1_i32_b64 s3, s[8:9]
	v_mov_b32_e32 v0, 0x2000
	v_mov_b32_e32 v1, s3
.LBB0_1345:
	s_or_b64 exec, exec, s[10:11]
	s_waitcnt vmcnt(0)

; __device__ __forceinline__ unsigned xb_ld(unsigned* p)              { return __hip_atomic_load(p, __ATOMIC_RELAXED, __HIP_MEMORY_SCOPE_AGENT); }
; __device__ __forceinline__ unsigned xb_add(unsigned* p, unsigned v) { return __hip_atomic_fetch_add(p, v, __ATOMIC_RELAXED, __HIP_MEMORY_SCOPE_AGENT); }
; #define XB_SPIN(cond, bar) do { unsigned _sp = 0; while (cond) { __builtin_amdgcn_s_sleep(1); \
;     if ((++_sp & 255u) == 0u) { if (xb_ld(&(bar)[XB_TMO])) break; if (_sp > XB_SPIN_CAP) { atomicAdd(&(bar)[XB_TMO], 1u); break; } } } } while (0)
; __device__ __forceinline__ void xcd_barrier(const XcdBarrier& b) {
;     ...
;         if (old + 1u == (gen + 1u) * nloc) {
;             __builtin_amdgcn_fence(__ATOMIC_RELEASE, "agent");
;             asm volatile("s_waitcnt vmcnt(0)" ::: "memory");
;             const unsigned og = xb_add(&bar[XB_TOP], 1u);
;             const unsigned tg = og / nx;
;             if (og + 1u == (tg + 1u) * nx) xb_add(&bar[XB_TOPGEN], 1u);
;             else XB_SPIN(xb_ld(&bar[XB_TOPGEN]) == tg, bar);
;             __builtin_amdgcn_fence(__ATOMIC_ACQUIRE, "agent");
;             xb_add(&bar[XB_XGEN(b.x)], 1u);
;             asm volatile("s_waitcnt vmcnt(0)" ::: "memory");
.LBB0_1422:
	s_or_b64 exec, exec, s[8:9]
	s_mov_b64 s[8:9], exec
	v_mbcnt_lo_u32_b32 v0, s8, 0
	v_mbcnt_hi_u32_b32 v0, s9, v0
	v_cmp_eq_u32_e32 vcc, 0, v0
	s_waitcnt vmcnt(0)
	buffer_inv sc1
	s_and_saveexec_b64 s[10:11], vcc
	s_cbranch_execz .LBB0_1424
	s_bcnt1_i32_b64 s3, s[8:9]
	v_mov_b32_e32 v0, 0x2000
	v_mov_b32_e32 v1, s3
.LBB0_1424:
	s_or_b64 exec, exec, s[10:11]
	s_waitcnt vmcnt(0)

; __device__ __forceinline__ unsigned xb_ld(unsigned* p)              { return __hip_atomic_load(p, __ATOMIC_RELAXED, __HIP_MEMORY_SCOPE_AGENT); }
; __device__ __forceinline__ unsigned xb_add(unsigned* p, unsigned v) { return __hip_atomic_fetch_add(p, v, __ATOMIC_RELAXED, __HIP_MEMORY_SCOPE_AGENT); }
; #define XB_SPIN(cond, bar) do { unsigned _sp = 0; while (cond) { __builtin_amdgcn_s_sleep(1); \
;     if ((++_sp & 255u) == 0u) { if (xb_ld(&(bar)[XB_TMO])) break; if (_sp > XB_SPIN_CAP) { atomicAdd(&(bar)[XB_TMO], 1u); break; } } } } while (0)
; __device__ __forceinline__ void xcd_barrier(const XcdBarrier& b) {
;     ...
;         if (old + 1u == (gen + 1u) * nloc) {
;             __builtin_amdgcn_fence(__ATOMIC_RELEASE, "agent");
;             asm volatile("s_waitcnt vmcnt(0)" ::: "memory");
;             const unsigned og = xb_add(&bar[XB_TOP], 1u);
;             const unsigned tg = og / nx;
;             if (og + 1u == (tg + 1u) * nx) xb_add(&bar[XB_TOPGEN], 1u);
;             else XB_SPIN(xb_ld(&bar[XB_TOPGEN]) == tg, bar);
;             __builtin_amdgcn_fence(__ATOMIC_ACQUIRE, "agent");
;             xb_add(&bar[XB_XGEN(b.x)], 1u);
;             asm volatile("s_waitcnt vmcnt(0)" ::: "memory");
.LBB0_1517:
	s_or_b64 exec, exec, s[8:9]
	s_mov_b64 s[8:9], exec
	v_mbcnt_lo_u32_b32 v0, s8, 0
	v_mbcnt_hi_u32_b32 v0, s9, v0
	v_cmp_eq_u32_e32 vcc, 0, v0
	s_waitcnt vmcnt(0)
	buffer_inv sc1
	s_and_saveexec_b64 s[10:11], vcc
	s_cbranch_execz .LBB0_1519
	s_bcnt1_i32_b64 s3, s[8:9]
	v_mov_b32_e32 v0, 0x2000
	v_mov_b32_e32 v1, s3
.LBB0_1519:
	s_or_b64 exec, exec, s[10:11]
	s_waitcnt vmcnt(0)

; __device__ __forceinline__ unsigned xb_ld(unsigned* p)              { return __hip_atomic_load(p, __ATOMIC_RELAXED, __HIP_MEMORY_SCOPE_AGENT); }
; __device__ __forceinline__ unsigned xb_add(unsigned* p, unsigned v) { return __hip_atomic_fetch_add(p, v, __ATOMIC_RELAXED, __HIP_MEMORY_SCOPE_AGENT); }
; #define XB_SPIN(cond, bar) do { unsigned _sp = 0; while (cond) { __builtin_amdgcn_s_sleep(1); \
;     if ((++_sp & 255u) == 0u) { if (xb_ld(&(bar)[XB_TMO])) break; if (_sp > XB_SPIN_CAP) { atomicAdd(&(bar)[XB_TMO], 1u); break; } } } } while (0)
; __device__ __forceinline__ void xcd_barrier(const XcdBarrier& b) {
;     ...
;         if (old + 1u == (gen + 1u) * nloc) {
;             __builtin_amdgcn_fence(__ATOMIC_RELEASE, "agent");
;             asm volatile("s_waitcnt vmcnt(0)" ::: "memory");
;             const unsigned og = xb_add(&bar[XB_TOP], 1u);
;             const unsigned tg = og / nx;
;             if (og + 1u == (tg + 1u) * nx) xb_add(&bar[XB_TOPGEN], 1u);
;             else XB_SPIN(xb_ld(&bar[XB_TOPGEN]) == tg, bar);
;             __builtin_amdgcn_fence(__ATOMIC_ACQUIRE, "agent");
;             xb_add(&bar[XB_XGEN(b.x)], 1u);
;             asm volatile("s_waitcnt vmcnt(0)" ::: "memory");
.LBB0_1592:
	s_or_b64 exec, exec, s[8:9]
	s_mov_b64 s[8:9], exec
	v_mbcnt_lo_u32_b32 v0, s8, 0
	v_mbcnt_hi_u32_b32 v0, s9, v0
	v_cmp_eq_u32_e32 vcc, 0, v0
	s_waitcnt vmcnt(0)
	buffer_inv sc1
	s_and_saveexec_b64 s[10:11], vcc
	s_cbranch_execz .LBB0_1594
	s_bcnt1_i32_b64 s3, s[8:9]
	v_mov_b32_e32 v0, 0x2000
	v_mov_b32_e32 v1, s3
.LBB0_1594:
	s_or_b64 exec, exec, s[10:11]
	s_waitcnt vmcnt(0)

; __device__ __forceinline__ unsigned xb_ld(unsigned* p)              { return __hip_atomic_load(p, __ATOMIC_RELAXED, __HIP_MEMORY_SCOPE_AGENT); }
; __device__ __forceinline__ unsigned xb_add(unsigned* p, unsigned v) { return __hip_atomic_fetch_add(p, v, __ATOMIC_RELAXED, __HIP_MEMORY_SCOPE_AGENT); }
; #define XB_SPIN(cond, bar) do { unsigned _sp = 0; while (cond) { __builtin_amdgcn_s_sleep(1); \
;     if ((++_sp & 255u) == 0u) { if (xb_ld(&(bar)[XB_TMO])) break; if (_sp > XB_SPIN_CAP) { atomicAdd(&(bar)[XB_TMO], 1u); break; } } } } while (0)
; __device__ __forceinline__ void xcd_barrier(const XcdBarrier& b) {
;     ...
;         if (old + 1u == (gen + 1u) * nloc) {
;             __builtin_amdgcn_fence(__ATOMIC_RELEASE, "agent");
;             asm volatile("s_waitcnt vmcnt(0)" ::: "memory");
;             const unsigned og = xb_add(&bar[XB_TOP], 1u);
;             const unsigned tg = og / nx;
;             if (og + 1u == (tg + 1u) * nx) xb_add(&bar[XB_TOPGEN], 1u);
;             else XB_SPIN(xb_ld(&bar[XB_TOPGEN]) == tg, bar);
;             __builtin_amdgcn_fence(__ATOMIC_ACQUIRE, "agent");
;             xb_add(&bar[XB_XGEN(b.x)], 1u);
;             asm volatile("s_waitcnt vmcnt(0)" ::: "memory");
.LBB0_1685:
	s_or_b64 exec, exec, s[8:9]
	s_mov_b64 s[8:9], exec
	v_mbcnt_lo_u32_b32 v0, s8, 0
	v_mbcnt_hi_u32_b32 v0, s9, v0
	v_cmp_eq_u32_e32 vcc, 0, v0
	s_waitcnt vmcnt(0)
	buffer_inv sc1
	s_and_saveexec_b64 s[10:11], vcc
	s_cbranch_execz .LBB0_1687
	s_bcnt1_i32_b64 s3, s[8:9]
	v_mov_b32_e32 v0, 0x2000
	v_mov_b32_e32 v1, s3
.LBB0_1687:
	s_or_b64 exec, exec, s[10:11]
	s_waitcnt vmcnt(0)

; __device__ __forceinline__ unsigned xb_ld(unsigned* p)              { return __hip_atomic_load(p, __ATOMIC_RELAXED, __HIP_MEMORY_SCOPE_AGENT); }
; __device__ __forceinline__ unsigned xb_add(unsigned* p, unsigned v) { return __hip_atomic_fetch_add(p, v, __ATOMIC_RELAXED, __HIP_MEMORY_SCOPE_AGENT); }
; #define XB_SPIN(cond, bar) do { unsigned _sp = 0; while (cond) { __builtin_amdgcn_s_sleep(1); \
;     if ((++_sp & 255u) == 0u) { if (xb_ld(&(bar)[XB_TMO])) break; if (_sp > XB_SPIN_CAP) { atomicAdd(&(bar)[XB_TMO], 1u); break; } } } } while (0)
; __device__ __forceinline__ void xcd_barrier(const XcdBarrier& b) {
;     ...
;         if (old + 1u == (gen + 1u) * nloc) {
;             __builtin_amdgcn_fence(__ATOMIC_RELEASE, "agent");
;             asm volatile("s_waitcnt vmcnt(0)" ::: "memory");
;             const unsigned og = xb_add(&bar[XB_TOP], 1u);
;             const unsigned tg = og / nx;
;             if (og + 1u == (tg + 1u) * nx) xb_add(&bar[XB_TOPGEN], 1u);
;             else XB_SPIN(xb_ld(&bar[XB_TOPGEN]) == tg, bar);
;             __builtin_amdgcn_fence(__ATOMIC_ACQUIRE, "agent");
;             xb_add(&bar[XB_XGEN(b.x)], 1u);
;             asm volatile("s_waitcnt vmcnt(0)" ::: "memory");
.LBB0_1781:
	s_or_b64 exec, exec, s[8:9]
	s_mov_b64 s[8:9], exec
	v_mbcnt_lo_u32_b32 v0, s8, 0
	v_mbcnt_hi_u32_b32 v0, s9, v0
	v_cmp_eq_u32_e32 vcc, 0, v0
	s_waitcnt vmcnt(0)
	buffer_inv sc1
	s_and_saveexec_b64 s[10:11], vcc
	s_cbranch_execz .LBB0_1783
	s_bcnt1_i32_b64 s3, s[8:9]
	v_mov_b32_e32 v0, 0x2000
	v_mov_b32_e32 v1, s3
.LBB0_1783:
	s_or_b64 exec, exec, s[10:11]
	s_waitcnt vmcnt(0)

; __device__ __forceinline__ unsigned xb_ld(unsigned* p)              { return __hip_atomic_load(p, __ATOMIC_RELAXED, __HIP_MEMORY_SCOPE_AGENT); }
; __device__ __forceinline__ unsigned xb_add(unsigned* p, unsigned v) { return __hip_atomic_fetch_add(p, v, __ATOMIC_RELAXED, __HIP_MEMORY_SCOPE_AGENT); }
; #define XB_SPIN(cond, bar) do { unsigned _sp = 0; while (cond) { __builtin_amdgcn_s_sleep(1); \
;     if ((++_sp & 255u) == 0u) { if (xb_ld(&(bar)[XB_TMO])) break; if (_sp > XB_SPIN_CAP) { atomicAdd(&(bar)[XB_TMO], 1u); break; } } } } while (0)
; __device__ __forceinline__ void xcd_barrier(const XcdBarrier& b) {
;     ...
;         if (old + 1u == (gen + 1u) * nloc) {
;             __builtin_amdgcn_fence(__ATOMIC_RELEASE, "agent");
;             asm volatile("s_waitcnt vmcnt(0)" ::: "memory");
;             const unsigned og = xb_add(&bar[XB_TOP], 1u);
;             const unsigned tg = og / nx;
;             if (og + 1u == (tg + 1u) * nx) xb_add(&bar[XB_TOPGEN], 1u);
;             else XB_SPIN(xb_ld(&bar[XB_TOPGEN]) == tg, bar);
;             __builtin_amdgcn_fence(__ATOMIC_ACQUIRE, "agent");
;             xb_add(&bar[XB_XGEN(b.x)], 1u);
;             asm volatile("s_waitcnt vmcnt(0)" ::: "memory");
.LBB0_1900:
	s_or_b64 exec, exec, s[8:9]
	s_mov_b64 s[8:9], exec
	v_mbcnt_lo_u32_b32 v0, s8, 0
	v_mbcnt_hi_u32_b32 v0, s9, v0
	v_cmp_eq_u32_e32 vcc, 0, v0
	s_waitcnt vmcnt(0)
	buffer_inv sc1
	s_and_saveexec_b64 s[10:11], vcc
	s_cbranch_execz .LBB0_1902
	s_bcnt1_i32_b64 s3, s[8:9]
	v_mov_b32_e32 v0, 0x2000
	v_mov_b32_e32 v1, s3
.LBB0_1902:
	s_or_b64 exec, exec, s[10:11]
	s_waitcnt vmcnt(0)

; __device__ __forceinline__ unsigned xb_ld(unsigned* p)              { return __hip_atomic_load(p, __ATOMIC_RELAXED, __HIP_MEMORY_SCOPE_AGENT); }
; __device__ __forceinline__ unsigned xb_add(unsigned* p, unsigned v) { return __hip_atomic_fetch_add(p, v, __ATOMIC_RELAXED, __HIP_MEMORY_SCOPE_AGENT); }
; #define XB_SPIN(cond, bar) do { unsigned _sp = 0; while (cond) { __builtin_amdgcn_s_sleep(1); \
;     if ((++_sp & 255u) == 0u) { if (xb_ld(&(bar)[XB_TMO])) break; if (_sp > XB_SPIN_CAP) { atomicAdd(&(bar)[XB_TMO], 1u); break; } } } } while (0)
; __device__ __forceinline__ void xcd_barrier(const XcdBarrier& b) {
;     ...
;         if (old + 1u == (gen + 1u) * nloc) {
;             __builtin_amdgcn_fence(__ATOMIC_RELEASE, "agent");
;             asm volatile("s_waitcnt vmcnt(0)" ::: "memory");
;             const unsigned og = xb_add(&bar[XB_TOP], 1u);
;             const unsigned tg = og / nx;
;             if (og + 1u == (tg + 1u) * nx) xb_add(&bar[XB_TOPGEN], 1u);
;             else XB_SPIN(xb_ld(&bar[XB_TOPGEN]) == tg, bar);
;             __builtin_amdgcn_fence(__ATOMIC_ACQUIRE, "agent");
;             xb_add(&bar[XB_XGEN(b.x)], 1u);
;             asm volatile("s_waitcnt vmcnt(0)" ::: "memory");
.LBB0_1997:
	s_or_b64 exec, exec, s[8:9]
	s_mov_b64 s[8:9], exec
	v_mbcnt_lo_u32_b32 v0, s8, 0
	v_mbcnt_hi_u32_b32 v0, s9, v0
	v_cmp_eq_u32_e32 vcc, 0, v0
	s_waitcnt vmcnt(0)
	buffer_inv sc1
	s_and_saveexec_b64 s[10:11], vcc
	s_cbranch_execz .LBB0_1999
	s_bcnt1_i32_b64 s3, s[8:9]
	v_mov_b32_e32 v0, 0x2000
	v_mov_b32_e32 v1, s3
.LBB0_1999:
	s_or_b64 exec, exec, s[10:11]
	s_waitcnt vmcnt(0)
